# dil_combine: the six o_g loads issued together with the lse loads (one round trip per token) on top of opt11
# speedup vs baseline: 1.0078x; 1.0008x over previous
; __device__ __forceinline__ unsigned pk2(float lo, float hi) { return f2bf(lo) | (f2bf(hi) << 16); }
; __device__ __forceinline__ void phase_dil_combine(const PT a, int lane, int gw, int ngw) {
;     ...
;     for (int tok = gw; tok < M; tok += ngw) {
;         const int h = lane >> 3;
;         const float l0 = lseb[((size_t)0 * M + tok) * 8 + h], l1 = lseb[((size_t)1 * M + tok) * 8 + h], l2 = lseb[((size_t)2 * M + tok) * 8 + h];
;         const float mx = fmaxf(l0, fmaxf(l1, l2)); float w0 = __expf(l0 - mx), w1 = __expf(l1 - mx), w2 = __expf(l2 - mx); const float iw = 1.0f / (w0 + w1 + w2); w0 *= iw; w1 *= iw; w2 *= iw;
;         const f32x4* p0 = (const f32x4*)(oag + ((size_t)0 * M + tok) * 512 + lane * 8); const f32x4* p1 = (const f32x4*)(oag + ((size_t)1 * M + tok) * 512 + lane * 8); const f32x4* p2 = (const f32x4*)(oag + ((size_t)2 * M + tok) * 512 + lane * 8);
;         const f32x4 x0 = w0 * p0[0] + w1 * p1[0] + w2 * p2[0], x1 = w0 * p0[1] + w1 * p1[1] + w2 * p2[1];
;         u32x4 o; o.x = pk2(x0.x, x0.y); o.y = pk2(x0.z, x0.w); o.z = pk2(x1.x, x1.y); o.w = pk2(x1.z, x1.w);
;         *(u32x4*)(oa + (size_t)tok * KCAT + lane * 8) = o;
;     }
.LBB0_106:
	s_nop 0
	v_lshl_add_u64 v[10:11], s[0:1], 0, v[8:9]
	v_add_co_u32_e32 v12, vcc, 0x2c000000, v10
	v_lshl_add_u64 v[30:31], s[0:1], 0, v[6:7]
	s_nop 0
	v_addc_co_u32_e32 v13, vcc, 0, v11, vcc
	global_load_dword v0, v[12:13], off
	v_add_co_u32_e32 v12, vcc, 0x2c040000, v10
	s_nop 1
	v_addc_co_u32_e32 v13, vcc, 0, v11, vcc
	v_add_co_u32_e32 v10, vcc, 0x2c080000, v10
	global_load_dword v12, v[12:13], off
	s_nop 0
	v_addc_co_u32_e32 v11, vcc, 0, v11, vcc
	global_load_dword v10, v[10:11], off
	s_mov_b64 s[14:15], 0x28000000
	v_lshl_add_u64 v[14:15], v[30:31], 0, s[14:15]
	v_lshl_add_u64 v[18:19], v[30:31], 0, s[14:15]
	s_mov_b64 s[14:15], 0x29000000
	v_lshl_add_u64 v[22:23], v[30:31], 0, s[14:15]
	v_lshl_add_u64 v[26:27], v[30:31], 0, s[14:15]
	s_mov_b64 s[14:15], 0x2a000000
	v_lshl_add_u64 v[38:39], v[30:31], 0, s[14:15]
	v_lshl_add_u64 v[42:43], v[30:31], 0, s[14:15]
	global_load_dwordx4 v[14:17], v[14:15], off
	global_load_dwordx4 v[18:21], v[18:19], off offset:16
	global_load_dwordx4 v[22:25], v[22:23], off
	global_load_dwordx4 v[26:29], v[26:27], off offset:16
	global_load_dwordx4 v[38:41], v[38:39], off
	global_load_dwordx4 v[42:45], v[42:43], off offset:16
	s_add_i32 s4, s4, s6
	v_lshl_add_u64 v[6:7], v[6:7], 0, s[10:11]
	v_lshl_add_u64 v[8:9], v[8:9], 0, s[12:13]
	s_cmpk_lt_i32 s4, 0x2000
	s_waitcnt vmcnt(6)
	v_max3_f32 v11, v0, v12, v10
	v_sub_f32_e32 v0, v0, v11
	v_sub_f32_e32 v12, v12, v11
	v_mul_f32_e32 v0, 0x3fb8aa3b, v0
	v_mul_f32_e32 v12, 0x3fb8aa3b, v12
	v_sub_f32_e32 v10, v10, v11
	v_exp_f32_e32 v0, v0
	v_exp_f32_e32 v12, v12
	v_mul_f32_e32 v10, 0x3fb8aa3b, v10
	v_exp_f32_e32 v10, v10
	s_nop 0
	v_add_f32_e32 v11, v0, v12
	v_add_f32_e32 v11, v10, v11
	v_div_scale_f32 v13, s[14:15], v11, v11, 1.0
	v_rcp_f32_e32 v46, v13
	s_nop 0
	v_fma_f32 v47, -v13, v46, 1.0
	v_fmac_f32_e32 v46, v47, v46
	v_div_scale_f32 v47, vcc, 1.0, v11, 1.0
	v_mul_f32_e32 v48, v47, v46
	v_fma_f32 v49, -v13, v48, v47
	v_fmac_f32_e32 v48, v49, v46
	v_fma_f32 v13, -v13, v48, v47
	s_nop 1
	v_div_fmas_f32 v13, v13, v46, v48
	v_div_fixup_f32 v11, v13, v11, 1.0
	v_mul_f32_e32 v12, v12, v11
	v_mul_f32_e32 v0, v0, v11
	v_mul_f32_e32 v10, v10, v11
	s_waitcnt vmcnt(0)
	v_pk_mul_f32 v[22:23], v[22:23], v[12:13] op_sel_hi:[1,0]
	s_nop 0
	v_pk_fma_f32 v[34:35], v[14:15], v[0:1], v[22:23] op_sel_hi:[1,0,1]
	v_pk_mul_f32 v[24:25], v[24:25], v[12:13] op_sel_hi:[1,0]
	s_nop 0
	v_pk_fma_f32 v[36:37], v[16:17], v[0:1], v[24:25] op_sel_hi:[1,0,1]
	v_pk_mul_f32 v[28:29], v[28:29], v[12:13] op_sel_hi:[1,0]
	v_pk_mul_f32 v[12:13], v[26:27], v[12:13] op_sel_hi:[1,0]
	v_pk_fma_f32 v[14:15], v[38:39], v[10:11], v[34:35] op_sel_hi:[1,0,1]
	v_pk_fma_f32 v[12:13], v[18:19], v[0:1], v[12:13] op_sel_hi:[1,0,1]
	v_pk_fma_f32 v[18:19], v[20:21], v[0:1], v[28:29] op_sel_hi:[1,0,1]
	v_bfe_u32 v0, v14, 16, 1
	v_pk_fma_f32 v[16:17], v[40:41], v[10:11], v[36:37] op_sel_hi:[1,0,1]
	v_pk_fma_f32 v[18:19], v[44:45], v[10:11], v[18:19] op_sel_hi:[1,0,1]
	v_pk_fma_f32 v[12:13], v[42:43], v[10:11], v[12:13] op_sel_hi:[1,0,1]
	v_add3_u32 v0, v14, v0, s72
	v_bfe_u32 v10, v15, 16, 1
	v_lshrrev_b32_e32 v0, 16, v0
	v_add3_u32 v10, v15, v10, s72
	v_and_or_b32 v10, v10, s97, v0
	v_bfe_u32 v0, v16, 16, 1
	v_add3_u32 v0, v16, v0, s72
	v_bfe_u32 v11, v17, 16, 1
	v_lshrrev_b32_e32 v0, 16, v0
	v_add3_u32 v11, v17, v11, s72
	v_and_or_b32 v11, v11, s97, v0
	v_bfe_u32 v0, v12, 16, 1
	v_add3_u32 v0, v12, v0, s72
	v_bfe_u32 v12, v13, 16, 1
	v_lshrrev_b32_e32 v0, 16, v0
	v_add3_u32 v12, v13, v12, s72
	v_and_or_b32 v12, v12, s97, v0
	v_bfe_u32 v0, v18, 16, 1
	v_add3_u32 v0, v18, v0, s72
	v_bfe_u32 v13, v19, 16, 1
	v_lshrrev_b32_e32 v0, 16, v0
	v_add3_u32 v13, v19, v13, s72
	v_and_or_b32 v13, v13, s97, v0
	v_lshl_add_u64 v[14:15], s[0:1], 0, v[4:5]
	v_lshl_add_u64 v[4:5], v[4:5], 0, s[8:9]
	global_store_dwordx4 v[14:15], v[10:13], off
	s_cbranch_scc1 .LBB0_106
